# tile order variant: 8 row panels x 4 column tiles per XCD round for ffn_in and a_in
# baseline (speedup 1.0000x reference)
.LBB0_66:
	s_or_b64 exec, exec, s[4:5]
	s_mov_b64 s[4:5], s[0:1]
	v_mov_b32_e32 v8, v157
	s_cmpk_lt_i32 s2, 0xb00
	s_cselect_b64 s[24:25], -1, 0
	s_cmpk_gt_i32 s2, 0xaff
	v_readfirstlane_b32 s20, v8
	s_cbranch_scc1 .LBB0_84
	v_lshlrev_b32_e32 v0, 4, v8
	v_add_u32_e32 v1, 0x2000, v0
	v_ashrrev_i32_e32 v2, 31, v1
	v_lshrrev_b32_e32 v2, 22, v2
	v_add_u32_e32 v2, v1, v2
	v_ashrrev_i32_e32 v9, 10, v2
	v_mul_i32_i24_e32 v2, 0x400, v9
	v_sub_u32_e32 v1, v1, v2
	v_lshrrev_b32_e32 v2, 4, v1
	v_bitop3_b32 v1, v2, v1, 32 bitop3:0x6c
	v_ashrrev_i32_e32 v2, 31, v1
	v_lshrrev_b32_e32 v2, 26, v2
	v_add_u32_e32 v2, v1, v2
	v_lshlrev_b32_e32 v3, 3, v9
	v_ashrrev_i32_e32 v10, 6, v2
	v_and_b32_e32 v3, -16, v3
	v_add_u32_e32 v3, v10, v3
	v_and_b32_e32 v4, 3, v10
	s_mov_b32 s8, 0x1fffe0
	v_lshrrev_b32_e32 v5, 2, v3
	v_lshlrev_b32_e32 v6, 1, v3
	v_and_b32_e32 v2, 0xc0, v2
	v_and_or_b32 v4, v3, s8, v4
	v_and_b32_e32 v5, 4, v5
	v_and_b32_e32 v6, 24, v6
	v_sub_u32_e32 v1, v1, v2
	v_mov_b32_e32 v2, 1
	v_or3_b32 v4, v4, v5, v6
	v_lshlrev_b32_e32 v5, 5, v9
	v_ashrrev_i16_sdwa v1, v2, sext(v1) dst_sel:DWORD dst_unused:UNUSED_PAD src0_sel:DWORD src1_sel:BYTE_0
	v_and_b32_e32 v5, 32, v5
	v_bfe_i32 v11, v1, 0, 16
	v_add_lshl_u32 v1, v5, v11, 1
	v_lshl_add_u32 v128, v4, 11, v1
	v_lshrrev_b32_e32 v250, 3, v157
	v_and_b32_e32 v251, 6, v250
	v_and_b32_e32 v252, 7, v157
	v_xor_b32_e32 v251, v251, v252
	v_lshlrev_b32_e32 v251, 4, v251
	v_and_b32_e32 v252, 12, v250
	v_lshlrev_b32_e32 v252, 1, v252
	v_and_b32_e32 v253, 16, v250
	v_lshrrev_b32_e32 v253, 2, v253
	v_or_b32_e32 v252, v252, v253
	v_and_b32_e32 v253, 35, v250
	v_or_b32_e32 v250, v252, v253
	v_mul_u32_u24_e32 v250, 0x800, v250
	v_add_u32_e32 v128, v250, v251
	v_add_u32_e32 v128, 0x20000, v128
	v_lshl_add_u32 v130, v3, 11, v1
	v_lshrrev_b32_e32 v250, 3, v157
	v_and_b32_e32 v251, 6, v250
	v_and_b32_e32 v252, 7, v157
	v_xor_b32_e32 v251, v251, v252
	v_lshlrev_b32_e32 v251, 4, v251
	v_mul_u32_u24_e32 v250, 0x800, v250
	v_add_u32_e32 v130, v250, v251
	v_add_u32_e32 v130, 0x20000, v130
	v_bfe_i32 v1, v8, 27, 1
	v_lshrrev_b32_e32 v1, 22, v1
	v_add_u32_e32 v1, v0, v1
	s_load_dwordx2 s[4:5], s[4:5], 0x80
	v_and_b32_e32 v1, 0xfffffc00, v1
	v_sub_u32_e32 v0, v0, v1
	v_lshrrev_b32_e32 v1, 4, v0
	v_ashrrev_i32_e32 v3, 31, v8
	v_bitop3_b32 v0, v1, v0, 32 bitop3:0x6c
	v_lshrrev_b32_e32 v3, 26, v3
	v_ashrrev_i32_e32 v1, 31, v0
	v_add_u32_e32 v3, v8, v3
	s_waitcnt lgkmcnt(0)
	s_add_u32 s3, s4, 0x6000000
	v_lshrrev_b32_e32 v1, 26, v1
	v_ashrrev_i32_e32 v13, 6, v3
	s_addc_u32 s35, s5, 0
	v_add_u32_e32 v1, v0, v1
	v_lshlrev_b32_e32 v3, 3, v13
	s_add_u32 s50, s4, 0x400000
	v_ashrrev_i32_e32 v12, 6, v1
	v_and_b32_e32 v3, -16, v3
	s_addc_u32 s51, s5, 0
	v_add_u32_e32 v3, v12, v3
	v_and_b32_e32 v4, 3, v12
	s_ashr_i32 s53, s2, 31
	v_and_or_b32 v4, v3, s8, v4
	s_lshr_b32 s8, s53, 29
	s_add_i32 s8, s2, s8
	s_ashr_i32 s17, s20, 6
	s_ashr_i32 s9, s8, 3
	s_and_b32 s8, s8, -8
	s_ashr_i32 s21, s20, 8
	s_lshl_b32 s52, s17, 10
	s_sub_i32 s8, s2, s8
	s_cmp_lt_i32 s8, 0
	s_movk_i32 s54, 0x161
	s_cselect_b32 s10, s54, 0x160
	s_mul_i32 s8, s10, s8
	s_add_i32 s8, s8, s9
	s_mul_hi_i32 s9, s8, 0x2e8ba2e9
	s_lshr_b32 s10, s9, 31
	s_ashr_i32 s9, s9, 3
	s_add_i32 s9, s9, s10
	s_lshl_b32 s10, s9, 1
	s_mul_i32 s9, s9, 44
	s_sub_i32 s8, s8, s9
	s_bfe_u32 s9, s8, 0x10007
	s_add_i32 s9, s8, s9
	s_bfe_i32 s11, s9, 0x80000
	s_and_b32 s9, s9, 0xfe
	s_sub_i32 s8, s8, s9
	s_sext_i32_i16 s11, s11
	s_sext_i32_i8 s8, s8
	v_lshrrev_b32_e32 v5, 2, v3
	v_lshlrev_b32_e32 v6, 1, v3
	v_and_b32_e32 v1, 0xc0, v1
	s_lshr_b32 s16, s11, 1
	s_add_i32 s44, s10, s8
	s_cmp_eq_u32 s42, 0x100
	s_cbranch_scc0 .Lwgm_p_0
	s_lshr_b32 s99, s2, 3
	s_and_b32 s44, s99, 7
	s_lshr_b32 s16, s99, 3
	s_and_b32 s98, s2, 7
	s_lshl_b32 s98, s98, 4
	s_add_i32 s44, s44, s98

.LBB0_72:
	s_add_i32 s59, s59, 1
	s_mul_i32 s4, s59, s62
	s_mul_hi_u32 s5, s59, s63
	s_add_i32 s5, s5, s4
	s_mul_i32 s4, s59, s63
	s_add_u32 s28, s4, s2
	s_addc_u32 s29, s5, s53
	v_cmp_gt_i64_e32 vcc, s[28:29], v[142:143]
	v_cmp_lt_i64_e64 s[4:5], s[28:29], v[140:141]
	s_cbranch_vccnz .LBB0_74
	s_cmp_eq_u32 s42, 0x100
	s_cbranch_scc0 .Lwgm_orig_0
	s_and_b32 s98, s2, 7
	s_lshr_b32 s99, s2, 3
	s_cmp_lt_u32 s59, 10
	s_cbranch_scc0 .Lwgm_tail_0
	s_and_b32 s100, s59, 1
	s_lshl_b32 s100, s100, 3
	s_and_b32 s101, s99, 7
	s_add_i32 s26, s100, s101
	s_lshr_b32 s100, s59, 1
	s_lshl_b32 s100, s100, 2
	s_lshr_b32 s101, s99, 3
	s_add_i32 s22, s100, s101
	s_branch .Lwgm_join_0
.Lwgm_tail_0:
	s_and_b32 s26, s99, 15
	s_lshr_b32 s101, s99, 4
	s_add_i32 s22, s101, 20

.LBB0_241:
	s_ashr_i32 s10, s12, 3
	s_add_i32 s10, s14, s10
	s_ashr_i32 s11, s10, 31
	s_lshr_b32 s11, s11, 27
	s_add_i32 s11, s10, s11
	s_ashr_i32 s12, s11, 5
	s_andn2_b32 s11, s11, 31
	s_sub_i32 s10, s10, s11
	s_bfe_u32 s11, s10, 0x10007
	s_add_i32 s11, s10, s11
	s_bfe_i32 s13, s11, 0x80000
	s_and_b32 s11, s11, 0xfe
	s_sub_i32 s10, s10, s11
	s_lshl_b32 s12, s12, 1
	s_sext_i32_i16 s13, s13
	s_sext_i32_i8 s10, s10
	s_add_i32 s14, s12, s10
	s_ashr_i32 s20, s13, 1
	s_cmp_eq_u32 s42, 0x100
	s_cbranch_scc0 .Lwgm_p_1
	s_lshr_b32 s99, s2, 3
	s_and_b32 s14, s99, 7
	s_lshr_b32 s20, s99, 3
	s_and_b32 s98, s2, 7
	s_lshl_b32 s98, s98, 4
	s_add_i32 s14, s14, s98

.LBB0_248:
	s_add_i32 s90, s90, 1
	s_mul_i32 s3, s90, s80
	s_mul_hi_u32 s12, s90, s81
	s_add_i32 s12, s12, s3
	s_mul_i32 s3, s90, s81
	s_add_u32 s62, s3, s2
	s_addc_u32 s63, s12, s82
	v_cmp_gt_i64_e32 vcc, s[62:63], v[174:175]
	v_cmp_lt_i64_e64 s[12:13], s[62:63], v[172:173]
	s_cbranch_vccnz .LBB0_254
	s_cmp_eq_u32 s42, 0x100
	s_cbranch_scc0 .Lwgm_orig_1
	s_and_b32 s98, s2, 7
	s_lshr_b32 s99, s2, 3
	s_and_b32 s100, s90, 1
	s_lshl_b32 s100, s100, 3
	s_and_b32 s101, s99, 7
	s_add_i32 s60, s100, s101
	s_lshr_b32 s100, s90, 1
	s_lshl_b32 s100, s100, 2
	s_lshr_b32 s101, s99, 3
	s_add_i32 s58, s100, s101
	s_lshl_b32 s98, s98, 4
	s_add_i32 s60, s60, s98
	s_branch .LBB0_254

.LBB0_517:
	s_or_b64 exec, exec, s[8:9]
	s_mov_b64 s[10:11], s[0:1]
	v_mov_b32_e32 v8, v157
	s_waitcnt lgkmcnt(0)
	v_cndmask_b32_e64 v0, 0, 1, s[24:25]
	s_barrier
	v_cmp_ne_u32_e64 s[8:9], 1, v0
	s_andn2_b64 vcc, exec, s[24:25]
	v_readfirstlane_b32 s24, v8
	s_cbranch_vccnz .LBB0_535
	v_lshlrev_b32_e32 v0, 4, v8
	v_add_u32_e32 v1, 0x2000, v0
	v_ashrrev_i32_e32 v2, 31, v1
	v_lshrrev_b32_e32 v2, 22, v2
	v_add_u32_e32 v2, v1, v2
	v_ashrrev_i32_e32 v9, 10, v2
	v_mul_i32_i24_e32 v2, 0x400, v9
	v_sub_u32_e32 v1, v1, v2
	v_lshrrev_b32_e32 v2, 4, v1
	v_bitop3_b32 v1, v2, v1, 32 bitop3:0x6c
	v_ashrrev_i32_e32 v2, 31, v1
	v_lshrrev_b32_e32 v2, 26, v2
	v_add_u32_e32 v2, v1, v2
	v_lshlrev_b32_e32 v3, 3, v9
	v_ashrrev_i32_e32 v10, 6, v2
	v_and_b32_e32 v3, -16, v3
	v_add_u32_e32 v3, v10, v3
	v_and_b32_e32 v4, 3, v10
	s_mov_b32 s12, 0x1fffe0
	v_lshrrev_b32_e32 v5, 2, v3
	v_lshlrev_b32_e32 v6, 1, v3
	v_and_b32_e32 v2, 0xc0, v2
	v_and_or_b32 v4, v3, s12, v4
	v_and_b32_e32 v5, 4, v5
	v_and_b32_e32 v6, 24, v6
	v_sub_u32_e32 v1, v1, v2
	v_mov_b32_e32 v2, 1
	v_or3_b32 v4, v4, v5, v6
	v_lshlrev_b32_e32 v5, 5, v9
	v_ashrrev_i16_sdwa v1, v2, sext(v1) dst_sel:DWORD dst_unused:UNUSED_PAD src0_sel:DWORD src1_sel:BYTE_0
	v_and_b32_e32 v5, 32, v5
	v_bfe_i32 v11, v1, 0, 16
	v_add_lshl_u32 v1, v5, v11, 1
	v_lshl_add_u32 v128, v4, 11, v1
	v_lshrrev_b32_e32 v250, 3, v157
	v_and_b32_e32 v251, 6, v250
	v_and_b32_e32 v252, 7, v157
	v_xor_b32_e32 v251, v251, v252
	v_lshlrev_b32_e32 v251, 4, v251
	v_and_b32_e32 v252, 12, v250
	v_lshlrev_b32_e32 v252, 1, v252
	v_and_b32_e32 v253, 16, v250
	v_lshrrev_b32_e32 v253, 2, v253
	v_or_b32_e32 v252, v252, v253
	v_and_b32_e32 v253, 35, v250
	v_or_b32_e32 v250, v252, v253
	v_mul_u32_u24_e32 v250, 0x800, v250
	v_add_u32_e32 v128, v250, v251
	v_add_u32_e32 v128, 0x20000, v128
	v_lshl_add_u32 v130, v3, 11, v1
	v_lshrrev_b32_e32 v250, 3, v157
	v_and_b32_e32 v251, 6, v250
	v_and_b32_e32 v252, 7, v157
	v_xor_b32_e32 v251, v251, v252
	v_lshlrev_b32_e32 v251, 4, v251
	v_mul_u32_u24_e32 v250, 0x800, v250
	v_add_u32_e32 v130, v250, v251
	v_add_u32_e32 v130, 0x20000, v130
	v_bfe_i32 v1, v8, 27, 1
	v_lshrrev_b32_e32 v1, 22, v1
	v_add_u32_e32 v1, v0, v1
	s_load_dwordx2 s[10:11], s[10:11], 0x80
	v_and_b32_e32 v1, 0xfffffc00, v1
	v_sub_u32_e32 v0, v0, v1
	v_lshrrev_b32_e32 v1, 4, v0
	v_ashrrev_i32_e32 v3, 31, v8
	v_bitop3_b32 v0, v1, v0, 32 bitop3:0x6c
	v_lshrrev_b32_e32 v3, 26, v3
	v_ashrrev_i32_e32 v1, 31, v0
	v_add_u32_e32 v3, v8, v3
	s_waitcnt lgkmcnt(0)
	s_add_u32 s3, s10, 0x6000000
	v_lshrrev_b32_e32 v1, 26, v1
	v_ashrrev_i32_e32 v13, 6, v3
	s_addc_u32 s35, s11, 0
	v_add_u32_e32 v1, v0, v1
	v_lshlrev_b32_e32 v3, 3, v13
	s_add_u32 s52, s10, 0xf00000
	v_ashrrev_i32_e32 v12, 6, v1
	v_and_b32_e32 v3, -16, v3
	s_addc_u32 s53, s11, 0
	v_add_u32_e32 v3, v12, v3
	v_and_b32_e32 v4, 3, v12
	s_ashr_i32 s55, s2, 31
	v_and_or_b32 v4, v3, s12, v4
	s_lshr_b32 s12, s55, 29
	s_add_i32 s12, s2, s12
	s_ashr_i32 s23, s24, 6
	s_ashr_i32 s13, s12, 3
	s_and_b32 s12, s12, -8
	s_ashr_i32 s25, s24, 8
	s_lshl_b32 s54, s23, 10
	s_sub_i32 s12, s2, s12
	s_cmp_lt_i32 s12, 0
	s_movk_i32 s56, 0x161
	s_cselect_b32 s14, s56, 0x160
	s_mul_i32 s12, s14, s12
	s_add_i32 s12, s12, s13
	s_mul_hi_i32 s13, s12, 0x2e8ba2e9
	s_lshr_b32 s14, s13, 31
	s_ashr_i32 s13, s13, 3
	s_add_i32 s13, s13, s14
	s_lshl_b32 s14, s13, 1
	s_mul_i32 s13, s13, 44
	s_sub_i32 s12, s12, s13
	s_bfe_u32 s13, s12, 0x10007
	s_add_i32 s13, s12, s13
	s_bfe_i32 s15, s13, 0x80000
	s_and_b32 s13, s13, 0xfe
	s_sub_i32 s12, s12, s13
	s_sext_i32_i16 s15, s15
	s_sext_i32_i8 s12, s12
	v_lshrrev_b32_e32 v5, 2, v3
	v_lshlrev_b32_e32 v6, 1, v3
	v_and_b32_e32 v1, 0xc0, v1
	s_lshr_b32 s22, s15, 1
	s_add_i32 s46, s14, s12
	s_cmp_eq_u32 s42, 0x100
	s_cbranch_scc0 .Lwgm_p_2
	s_lshr_b32 s99, s2, 3
	s_and_b32 s46, s99, 7
	s_lshr_b32 s22, s99, 3
	s_and_b32 s98, s2, 7
	s_lshl_b32 s98, s98, 4
	s_add_i32 s46, s46, s98

.LBB0_523:
	s_add_i32 s61, s61, 1
	s_mul_i32 s10, s61, s64
	s_mul_hi_u32 s11, s61, s65
	s_add_i32 s11, s11, s10
	s_mul_i32 s10, s61, s65
	s_add_u32 s30, s10, s2
	s_addc_u32 s31, s11, s55
	v_cmp_gt_i64_e32 vcc, s[30:31], v[142:143]
	v_cmp_lt_i64_e64 s[10:11], s[30:31], v[140:141]
	s_cbranch_vccnz .LBB0_525
	s_cmp_eq_u32 s42, 0x100
	s_cbranch_scc0 .Lwgm_orig_2
	s_and_b32 s98, s2, 7
	s_lshr_b32 s99, s2, 3
	s_cmp_lt_u32 s61, 10
	s_cbranch_scc0 .Lwgm_tail_2
	s_and_b32 s100, s61, 1
	s_lshl_b32 s100, s100, 3
	s_and_b32 s101, s99, 7
	s_add_i32 s28, s100, s101
	s_lshr_b32 s100, s61, 1
	s_lshl_b32 s100, s100, 2
	s_lshr_b32 s101, s99, 3
	s_add_i32 s26, s100, s101
	s_branch .Lwgm_join_2
.Lwgm_tail_2:
	s_and_b32 s28, s99, 15
	s_lshr_b32 s101, s99, 4
	s_add_i32 s26, s101, 20

.LBB0_687:
	s_or_b64 exec, exec, s[10:11]
	s_mov_b64 s[10:11], s[0:1]
	v_mov_b32_e32 v8, v157
	s_waitcnt lgkmcnt(0)
	s_barrier
	s_and_b64 vcc, exec, s[8:9]
	v_readfirstlane_b32 s24, v8
	s_cbranch_vccnz .LBB0_705
	v_lshlrev_b32_e32 v0, 4, v8
	v_add_u32_e32 v1, 0x2000, v0
	v_ashrrev_i32_e32 v2, 31, v1
	v_lshrrev_b32_e32 v2, 22, v2
	v_add_u32_e32 v2, v1, v2
	v_ashrrev_i32_e32 v9, 10, v2
	v_mul_i32_i24_e32 v2, 0x400, v9
	v_sub_u32_e32 v1, v1, v2
	v_lshrrev_b32_e32 v2, 4, v1
	v_bitop3_b32 v1, v2, v1, 32 bitop3:0x6c
	v_ashrrev_i32_e32 v2, 31, v1
	v_lshrrev_b32_e32 v2, 26, v2
	v_add_u32_e32 v2, v1, v2
	v_lshlrev_b32_e32 v3, 3, v9
	v_ashrrev_i32_e32 v10, 6, v2
	v_and_b32_e32 v3, -16, v3
	v_add_u32_e32 v3, v10, v3
	v_and_b32_e32 v4, 3, v10
	s_mov_b32 s12, 0x1fffe0
	v_lshrrev_b32_e32 v5, 2, v3
	v_lshlrev_b32_e32 v6, 1, v3
	v_and_b32_e32 v2, 0xc0, v2
	v_and_or_b32 v4, v3, s12, v4
	v_and_b32_e32 v5, 4, v5
	v_and_b32_e32 v6, 24, v6
	v_sub_u32_e32 v1, v1, v2
	v_mov_b32_e32 v2, 1
	v_or3_b32 v4, v4, v5, v6
	v_lshlrev_b32_e32 v5, 5, v9
	v_ashrrev_i16_sdwa v1, v2, sext(v1) dst_sel:DWORD dst_unused:UNUSED_PAD src0_sel:DWORD src1_sel:BYTE_0
	v_and_b32_e32 v5, 32, v5
	v_bfe_i32 v11, v1, 0, 16
	v_add_lshl_u32 v1, v5, v11, 1
	v_lshl_add_u32 v128, v4, 11, v1
	v_lshrrev_b32_e32 v250, 3, v157
	v_and_b32_e32 v251, 6, v250
	v_and_b32_e32 v252, 7, v157
	v_xor_b32_e32 v251, v251, v252
	v_lshlrev_b32_e32 v251, 4, v251
	v_and_b32_e32 v252, 12, v250
	v_lshlrev_b32_e32 v252, 1, v252
	v_and_b32_e32 v253, 16, v250
	v_lshrrev_b32_e32 v253, 2, v253
	v_or_b32_e32 v252, v252, v253
	v_and_b32_e32 v253, 35, v250
	v_or_b32_e32 v250, v252, v253
	v_mul_u32_u24_e32 v250, 0x800, v250
	v_add_u32_e32 v128, v250, v251
	v_add_u32_e32 v128, 0x20000, v128
	v_lshl_add_u32 v130, v3, 11, v1
	v_lshrrev_b32_e32 v250, 3, v157
	v_and_b32_e32 v251, 6, v250
	v_and_b32_e32 v252, 7, v157
	v_xor_b32_e32 v251, v251, v252
	v_lshlrev_b32_e32 v251, 4, v251
	v_mul_u32_u24_e32 v250, 0x800, v250
	v_add_u32_e32 v130, v250, v251
	v_add_u32_e32 v130, 0x20000, v130
	v_bfe_i32 v1, v8, 27, 1
	v_lshrrev_b32_e32 v1, 22, v1
	v_add_u32_e32 v1, v0, v1
	s_load_dwordx2 s[10:11], s[10:11], 0x80
	v_and_b32_e32 v1, 0xfffffc00, v1
	v_sub_u32_e32 v0, v0, v1
	v_lshrrev_b32_e32 v1, 4, v0
	v_ashrrev_i32_e32 v3, 31, v8
	v_bitop3_b32 v0, v1, v0, 32 bitop3:0x6c
	v_lshrrev_b32_e32 v3, 26, v3
	v_ashrrev_i32_e32 v1, 31, v0
	v_add_u32_e32 v3, v8, v3
	s_waitcnt lgkmcnt(0)
	s_add_u32 s3, s10, 0x6000000
	v_lshrrev_b32_e32 v1, 26, v1
	v_ashrrev_i32_e32 v13, 6, v3
	s_addc_u32 s35, s11, 0
	v_add_u32_e32 v1, v0, v1
	v_lshlrev_b32_e32 v3, 3, v13
	s_add_u32 s52, s10, 0x1a00000
	v_ashrrev_i32_e32 v12, 6, v1
	v_and_b32_e32 v3, -16, v3
	s_addc_u32 s53, s11, 0
	v_add_u32_e32 v3, v12, v3
	v_and_b32_e32 v4, 3, v12
	s_ashr_i32 s55, s2, 31
	v_and_or_b32 v4, v3, s12, v4
	s_lshr_b32 s12, s55, 29
	s_add_i32 s12, s2, s12
	s_ashr_i32 s23, s24, 6
	s_ashr_i32 s13, s12, 3
	s_and_b32 s12, s12, -8
	s_ashr_i32 s25, s24, 8
	s_lshl_b32 s54, s23, 10
	s_sub_i32 s12, s2, s12
	s_cmp_lt_i32 s12, 0
	s_movk_i32 s56, 0x161
	s_cselect_b32 s14, s56, 0x160
	s_mul_i32 s12, s14, s12
	s_add_i32 s12, s12, s13
	s_mul_hi_i32 s13, s12, 0x2e8ba2e9
	s_lshr_b32 s14, s13, 31
	s_ashr_i32 s13, s13, 3
	s_add_i32 s13, s13, s14
	s_lshl_b32 s14, s13, 1
	s_mul_i32 s13, s13, 44
	s_sub_i32 s12, s12, s13
	s_bfe_u32 s13, s12, 0x10007
	s_add_i32 s13, s12, s13
	s_bfe_i32 s15, s13, 0x80000
	s_and_b32 s13, s13, 0xfe
	s_sub_i32 s12, s12, s13
	s_sext_i32_i16 s15, s15
	s_sext_i32_i8 s12, s12
	v_lshrrev_b32_e32 v5, 2, v3
	v_lshlrev_b32_e32 v6, 1, v3
	v_and_b32_e32 v1, 0xc0, v1
	s_lshr_b32 s22, s15, 1
	s_add_i32 s46, s14, s12
	s_cmp_eq_u32 s42, 0x100
	s_cbranch_scc0 .Lwgm_p_3
	s_lshr_b32 s99, s2, 3
	s_and_b32 s46, s99, 7
	s_lshr_b32 s22, s99, 3
	s_and_b32 s98, s2, 7
	s_lshl_b32 s98, s98, 4
	s_add_i32 s46, s46, s98

.LBB0_1088:
	s_or_b64 exec, exec, s[6:7]
	s_mov_b64 s[6:7], s[0:1]
	v_mov_b32_e32 v8, v157
	s_waitcnt lgkmcnt(0)
	s_barrier
	s_and_b64 vcc, exec, s[8:9]
	v_readfirstlane_b32 s20, v8
	s_cbranch_vccnz .LBB0_1106
	v_lshlrev_b32_e32 v0, 4, v8
	v_add_u32_e32 v1, 0x2000, v0
	v_ashrrev_i32_e32 v2, 31, v1
	v_lshrrev_b32_e32 v2, 22, v2
	v_add_u32_e32 v2, v1, v2
	v_ashrrev_i32_e32 v9, 10, v2
	v_mul_i32_i24_e32 v2, 0x400, v9
	v_sub_u32_e32 v1, v1, v2
	v_lshrrev_b32_e32 v2, 4, v1
	v_bitop3_b32 v1, v2, v1, 32 bitop3:0x6c
	v_ashrrev_i32_e32 v2, 31, v1
	v_lshrrev_b32_e32 v2, 26, v2
	v_add_u32_e32 v2, v1, v2
	v_lshlrev_b32_e32 v3, 3, v9
	v_ashrrev_i32_e32 v10, 6, v2
	v_and_b32_e32 v3, -16, v3
	v_add_u32_e32 v3, v10, v3
	v_and_b32_e32 v4, 3, v10
	s_mov_b32 s8, 0x1fffe0
	v_lshrrev_b32_e32 v5, 2, v3
	v_lshlrev_b32_e32 v6, 1, v3
	v_and_b32_e32 v2, 0xc0, v2
	v_and_or_b32 v4, v3, s8, v4
	v_and_b32_e32 v5, 4, v5
	v_and_b32_e32 v6, 24, v6
	v_sub_u32_e32 v1, v1, v2
	v_mov_b32_e32 v2, 1
	v_or3_b32 v4, v4, v5, v6
	v_lshlrev_b32_e32 v5, 5, v9
	v_ashrrev_i16_sdwa v1, v2, sext(v1) dst_sel:DWORD dst_unused:UNUSED_PAD src0_sel:DWORD src1_sel:BYTE_0
	v_and_b32_e32 v5, 32, v5
	v_bfe_i32 v11, v1, 0, 16
	v_add_lshl_u32 v1, v5, v11, 1
	v_lshl_add_u32 v128, v4, 11, v1
	v_lshrrev_b32_e32 v250, 3, v157
	v_and_b32_e32 v251, 6, v250
	v_and_b32_e32 v252, 7, v157
	v_xor_b32_e32 v251, v251, v252
	v_lshlrev_b32_e32 v251, 4, v251
	v_and_b32_e32 v252, 12, v250
	v_lshlrev_b32_e32 v252, 1, v252
	v_and_b32_e32 v253, 16, v250
	v_lshrrev_b32_e32 v253, 2, v253
	v_or_b32_e32 v252, v252, v253
	v_and_b32_e32 v253, 35, v250
	v_or_b32_e32 v250, v252, v253
	v_mul_u32_u24_e32 v250, 0x800, v250
	v_add_u32_e32 v128, v250, v251
	v_add_u32_e32 v128, 0x20000, v128
	v_lshl_add_u32 v130, v3, 11, v1
	v_lshrrev_b32_e32 v250, 3, v157
	v_and_b32_e32 v251, 6, v250
	v_and_b32_e32 v252, 7, v157
	v_xor_b32_e32 v251, v251, v252
	v_lshlrev_b32_e32 v251, 4, v251
	v_mul_u32_u24_e32 v250, 0x800, v250
	v_add_u32_e32 v130, v250, v251
	v_add_u32_e32 v130, 0x20000, v130
	v_bfe_i32 v1, v8, 27, 1
	v_lshrrev_b32_e32 v1, 22, v1
	v_add_u32_e32 v1, v0, v1
	s_load_dwordx2 s[6:7], s[6:7], 0x80
	v_and_b32_e32 v1, 0xfffffc00, v1
	v_sub_u32_e32 v0, v0, v1
	v_lshrrev_b32_e32 v1, 4, v0
	v_ashrrev_i32_e32 v3, 31, v8
	v_bitop3_b32 v0, v1, v0, 32 bitop3:0x6c
	v_lshrrev_b32_e32 v3, 26, v3
	v_ashrrev_i32_e32 v1, 31, v0
	v_add_u32_e32 v3, v8, v3
	s_waitcnt lgkmcnt(0)
	s_add_u32 s3, s6, 0x6000000
	v_lshrrev_b32_e32 v1, 26, v1
	v_ashrrev_i32_e32 v13, 6, v3
	s_addc_u32 s33, s7, 0
	v_add_u32_e32 v1, v0, v1
	v_lshlrev_b32_e32 v3, 3, v13
	s_add_u32 s35, s6, 0x2500000
	v_ashrrev_i32_e32 v12, 6, v1
	v_and_b32_e32 v3, -16, v3
	s_addc_u32 s48, s7, 0
	v_add_u32_e32 v3, v12, v3
	v_and_b32_e32 v4, 3, v12
	s_ashr_i32 s50, s2, 31
	v_and_or_b32 v4, v3, s8, v4
	s_lshr_b32 s8, s50, 29
	s_add_i32 s8, s2, s8
	s_ashr_i32 s17, s20, 6
	s_ashr_i32 s9, s8, 3
	s_and_b32 s8, s8, -8
	s_ashr_i32 s21, s20, 8
	s_lshl_b32 s49, s17, 10
	s_sub_i32 s8, s2, s8
	s_cmp_lt_i32 s8, 0
	s_movk_i32 s51, 0x161
	s_cselect_b32 s10, s51, 0x160
	s_mul_i32 s8, s10, s8
	s_add_i32 s8, s8, s9
	s_mul_hi_i32 s9, s8, 0x2e8ba2e9
	s_lshr_b32 s10, s9, 31
	s_ashr_i32 s9, s9, 3
	s_add_i32 s9, s9, s10
	s_lshl_b32 s10, s9, 1
	s_mul_i32 s9, s9, 44
	s_sub_i32 s8, s8, s9
	s_bfe_u32 s9, s8, 0x10007
	s_add_i32 s9, s8, s9
	s_bfe_i32 s11, s9, 0x80000
	s_and_b32 s9, s9, 0xfe
	s_sub_i32 s8, s8, s9
	s_sext_i32_i16 s11, s11
	s_sext_i32_i8 s8, s8
	v_lshrrev_b32_e32 v5, 2, v3
	v_lshlrev_b32_e32 v6, 1, v3
	v_and_b32_e32 v1, 0xc0, v1
	s_lshr_b32 s16, s11, 1
	s_add_i32 s30, s10, s8
	s_cmp_eq_u32 s42, 0x100
	s_cbranch_scc0 .Lwgm_p_4
	s_lshr_b32 s99, s2, 3
	s_and_b32 s30, s99, 7
	s_lshr_b32 s16, s99, 3
	s_and_b32 s98, s2, 7
	s_lshl_b32 s98, s98, 4
	s_add_i32 s30, s30, s98

.LBB0_1094:
	s_add_i32 s56, s56, 1
	s_mul_i32 s6, s56, s59
	s_mul_hi_u32 s7, s56, s60
	s_add_i32 s7, s7, s6
	s_mul_i32 s6, s56, s60
	s_add_u32 s26, s6, s2
	s_addc_u32 s27, s7, s50
	v_cmp_gt_i64_e32 vcc, s[26:27], v[142:143]
	v_cmp_lt_i64_e64 s[6:7], s[26:27], v[140:141]
	s_cbranch_vccnz .LBB0_1096
	s_cmp_eq_u32 s42, 0x100
	s_cbranch_scc0 .Lwgm_orig_4
	s_and_b32 s98, s2, 7
	s_lshr_b32 s99, s2, 3
	s_cmp_lt_u32 s56, 10
	s_cbranch_scc0 .Lwgm_tail_4
	s_and_b32 s100, s56, 1
	s_lshl_b32 s100, s100, 3
	s_and_b32 s101, s99, 7
	s_add_i32 s24, s100, s101
	s_lshr_b32 s100, s56, 1
	s_lshl_b32 s100, s100, 2
	s_lshr_b32 s101, s99, 3
	s_add_i32 s22, s100, s101
	s_branch .Lwgm_join_4
.Lwgm_tail_4:
	s_and_b32 s24, s99, 15
	s_lshr_b32 s101, s99, 4
	s_add_i32 s22, s101, 20
